# x prefetch alone on the GLU phase's idle workgroups; all weight transposes on the out_proj phase's idle workgroups
# speedup vs baseline: 1.0051x; 1.0051x over previous
.Lp6_tr:
	v_readfirstlane_b32 s45, v170
	s_branch .Lpf7
.Lp7_tr:
	s_mov_b64 s[16:17], s[0:1]
	s_load_dwordx2 s[18:19], s[0:1], 0xe8
	s_sub_i32 s28, s2, 0xc0
	s_movk_i32 s45, 0x40
	s_movk_i32 s32, 0x1ff
	s_waitcnt lgkmcnt(0)
	s_add_u32 s20, s18, 0x7bc000
	s_addc_u32 s21, s19, 0
	v_mov_b32_e32 v0, v170
	s_cmpk_gt_i32 s28, 0x1ff
	s_cbranch_scc1 .Lp6_ret
	v_add_u32_e32 v3, 0x200, v0
	v_ashrrev_i32_e32 v5, 6, v3
	v_add_u32_e32 v3, 0x400, v0
	v_ashrrev_i32_e32 v6, 6, v3
	v_add_u32_e32 v3, 0x600, v0
	v_ashrrev_i32_e32 v7, 6, v3
	v_add_u32_e32 v3, 0x800, v0
	v_ashrrev_i32_e32 v8, 6, v3
	v_add_u32_e32 v3, 0xa00, v0
	s_add_u32 s4, s18, 0x1ebc000
	v_ashrrev_i32_e32 v9, 6, v3
	v_add_u32_e32 v3, 0xc00, v0
	s_addc_u32 s5, s19, 0
	v_ashrrev_i32_e32 v10, 6, v3
	v_add_u32_e32 v3, 0xe00, v0
	s_add_u32 s29, s18, 0xebc000
	v_ashrrev_i32_e32 v11, 6, v3
	v_bfe_u32 v3, v0, 4, 2
	v_lshlrev_b32_e32 v12, 4, v0
	s_addc_u32 s30, s19, 0
	v_mul_u32_u24_e32 v3, 0x4100, v3
	v_and_b32_e32 v12, 0xf0, v12
	s_add_u32 s31, s18, 0xe3c000
	v_lshlrev_b32_e32 v1, 2, v0
	v_ashrrev_i32_e32 v4, 6, v0
	v_add3_u32 v3, 0, v3, v12
	v_ashrrev_i32_e32 v12, 3, v0
	v_lshlrev_b32_e32 v0, 3, v0
	s_addc_u32 s35, s19, 0
	v_and_b32_e32 v24, 56, v0
	s_add_u32 s6, s18, 0xdbc000
	v_mul_u32_u24_e32 v0, 0x41, v24
	s_addc_u32 s7, s19, 0
	s_movk_i32 s10, 0x104
	v_lshlrev_b32_e32 v14, 2, v12
	v_lshlrev_b32_e32 v0, 2, v0
	s_add_u32 s8, s18, 0xbbc000
	v_and_b32_e32 v2, 0xfc, v1
	v_mov_b32_e32 v1, 0
	v_mul_lo_u32 v15, v4, s10
	v_mul_lo_u32 v16, v5, s10
	v_mul_lo_u32 v17, v6, s10
	v_mul_lo_u32 v18, v7, s10
	v_mul_lo_u32 v19, v8, s10
	v_mul_lo_u32 v20, v9, s10
	v_mul_lo_u32 v21, v10, s10
	v_mul_lo_u32 v22, v11, s10
	v_add3_u32 v13, 0, v14, v0
	v_add3_u32 v14, 0, v0, v14
	s_addc_u32 s9, s19, 0
	s_mov_b32 s11, 0
	s_movk_i32 s36, 0xe0
	v_lshlrev_b32_e32 v0, 2, v2
	v_add_u32_e32 v15, v3, v15
	v_add_u32_e32 v16, v3, v16
	v_add_u32_e32 v17, v3, v17
	v_add_u32_e32 v18, v3, v18
	v_add_u32_e32 v19, v3, v19
	v_add_u32_e32 v20, v3, v20
	v_add_u32_e32 v21, v3, v21
	v_add_u32_e32 v22, v3, v22
	v_lshlrev_b32_e32 v2, 1, v24
	v_mov_b32_e32 v3, v1
	v_add_u32_e32 v23, 0x400, v13
	v_add_u32_e32 v24, 0x400, v14
	v_add_u32_e32 v25, 0x4000, v13
	v_add_u32_e32 v26, 0x4200, v14
	v_add_u32_e32 v27, 0x4400, v13
	v_add_u32_e32 v28, 0x4600, v14
	v_add_u32_e32 v29, 0x8200, v13
	v_add_u32_e32 v30, 0x8200, v14
	v_add_u32_e32 v31, 0x8600, v13
	v_add_u32_e32 v32, 0x8600, v14
	v_add_u32_e32 v33, 0xc200, v13
	v_add_u32_e32 v34, 0xc400, v14
	v_add_u32_e32 v35, 0xc600, v13
	v_add_u32_e32 v36, 0xc800, v14
	s_mov_b32 s37, s28
	s_branch .LBB0_804

.Lp6_ret:
	s_mov_b64 exec, -1
	s_mov_b64 s[14:15], 0
	s_branch .LBB0_1246
